# hand EpiRes epilogue: 16 residual loads up front, counted vmcnt per row group
# baseline (speedup 1.0000x reference)
; #define ER_LOAD(q) do { _Pragma("unroll") for (int bj = 0; bj < 2; ++bj) t[(q) & 3][bj] = *(const u32x4*)(base + ER_OFF(q, bj)); } while (0)
; #define ER_ADD(q) do { _Pragma("unroll") for (int bj = 0; bj < 2; ++bj) { f32x4& a0 = acc[(q) >> 2][bj][(q) & 3][0]; f32x4& a1 = acc[(q) >> 2][bj][(q) & 3][1]; const u32x4 p = t[(q) & 3][bj]; \
;             a0[0] += bf_lo(p.x); a0[1] += bf_hi(p.x); a0[2] += bf_lo(p.y); a0[3] += bf_hi(p.y); a1[0] += bf_lo(p.z); a1[1] += bf_hi(p.z); a1[2] += bf_lo(p.w); a1[3] += bf_hi(p.w); } } while (0)
;     __device__ __forceinline__ void operator()(f32x4 (&acc)[2][2][4][2], const Unit& u, int wr, int wc, int fr, int fq) const {
;         const int row0 = u.pm * BM + wr * 64 + fr, col0 = u.pn * BM + wc * 32 + 8 * fq; const unsigned off0 = (unsigned)row0 * 1024u + (unsigned)col0;
;         u32x4 t[4][2];
;     ...
; #pragma unroll
;         for (int q = 0; q < 4; ++q) ER_LOAD(q);
; #pragma unroll
;         for (int q = 0; q < 4; ++q) ER_ADD(q);
; #pragma unroll
;         for (int q = 4; q < 8; ++q) ER_LOAD(q);
; #pragma unroll
;         for (int q = 0; q < 4; ++q) ER_STORE(q);
; #pragma unroll
;         for (int q = 4; q < 8; ++q) { ER_ADD(q); ER_STORE(q); }
.LBB0_276:
	v_lshrrev_b32_e32 v240, 8, v170
	v_and_b32_e32 v241, 15, v170
	v_lshl_add_u32 v240, v240, 6, v241
	s_lshl_b32 s98, s67, 8
	v_add_u32_e32 v240, s98, v240
	v_bfe_u32 v241, v170, 6, 2
	v_bfe_u32 v242, v170, 4, 2
	v_cmp_eq_u32_e32 vcc, 0, v242
	v_lshlrev_b32_e32 v241, 5, v241
	v_lshl_or_b32 v241, v242, 3, v241
	s_lshl_b32 s98, s66, 8
	v_add_u32_e32 v241, s98, v241
	v_lshl_add_u32 v241, v240, 10, v241
	v_lshlrev_b32_e32 v216, 1, v241
	v_mov_b32_e32 v217, 0
	v_lshl_add_u64 v[218:219], v[216:217], 0, s[42:43]
	v_lshl_add_u64 v[216:217], v[216:217], 0, v[176:177]
	v_lshlrev_b32_e32 v220, 3, v240
	v_mov_b32_e32 v221, 0
	v_lshl_add_u64 v[220:221], v[220:221], 0, s[40:41]
	s_mov_b32 s98, 0x8000
	s_mov_b32 s99, 0
	global_load_dwordx4 v[128:131], v[216:217], off
	global_load_dwordx4 v[132:135], v[216:217], off offset:256
	v_lshl_add_u64 v[216:217], v[216:217], 0, s[98:99]
	global_load_dwordx4 v[136:139], v[216:217], off
	global_load_dwordx4 v[140:143], v[216:217], off offset:256
	v_lshl_add_u64 v[216:217], v[216:217], 0, s[98:99]
	global_load_dwordx4 v[144:147], v[216:217], off
	global_load_dwordx4 v[148:151], v[216:217], off offset:256
	v_lshl_add_u64 v[216:217], v[216:217], 0, s[98:99]
	global_load_dwordx4 v[152:155], v[216:217], off
	global_load_dwordx4 v[156:159], v[216:217], off offset:256
	v_lshl_add_u64 v[216:217], v[216:217], 0, s[98:99]
	v_lshl_add_u64 v[216:217], v[216:217], 0, s[98:99]
	v_lshl_add_u64 v[216:217], v[216:217], 0, s[98:99]
	v_lshl_add_u64 v[216:217], v[216:217], 0, s[98:99]
	v_lshl_add_u64 v[216:217], v[216:217], 0, s[98:99]
	global_load_dwordx4 v[160:163], v[216:217], off
	global_load_dwordx4 v[164:167], v[216:217], off offset:256
	v_lshl_add_u64 v[216:217], v[216:217], 0, s[98:99]
	global_load_dwordx4 v[192:195], v[216:217], off
	global_load_dwordx4 v[196:199], v[216:217], off offset:256
	v_lshl_add_u64 v[216:217], v[216:217], 0, s[98:99]
	global_load_dwordx4 v[200:203], v[216:217], off
	global_load_dwordx4 v[204:207], v[216:217], off offset:256
	v_lshl_add_u64 v[216:217], v[216:217], 0, s[98:99]
	global_load_dwordx4 v[208:211], v[216:217], off
	global_load_dwordx4 v[212:215], v[216:217], off offset:256
	v_cmp_lt_i32_e64 s[10:11], v233, v228
	s_nop 1
	v_cndmask_b32_e64 v226, v225, v233, s[10:11]
	v_lshlrev_b32_e32 v226, 2, v226
	v_cmp_lt_i32_e64 s[10:11], v234, v228
	s_nop 1
	v_cndmask_b32_e64 v227, v225, v234, s[10:11]
	v_lshlrev_b32_e32 v227, 2, v227
	s_waitcnt vmcnt(14)
	v_lshlrev_b32_e32 v241, 16, v128
	v_and_b32_e32 v242, 0xffff0000, v128
	v_add_f32_e32 v124, v124, v241
	v_add_f32_e32 v125, v125, v242
	v_lshlrev_b32_e32 v241, 16, v129
	v_and_b32_e32 v242, 0xffff0000, v129
	v_add_f32_e32 v126, v126, v241
	v_add_f32_e32 v127, v127, v242
	v_lshlrev_b32_e32 v241, 16, v130
	v_and_b32_e32 v242, 0xffff0000, v130
	v_add_f32_e32 v120, v120, v241
	v_add_f32_e32 v121, v121, v242
	v_lshlrev_b32_e32 v241, 16, v131
	v_and_b32_e32 v242, 0xffff0000, v131
	v_add_f32_e32 v122, v122, v241
	v_add_f32_e32 v123, v123, v242
	v_cvt_pk_bf16_f32 v124, v124, v125
	v_cvt_pk_bf16_f32 v125, v126, v127
	v_cvt_pk_bf16_f32 v126, v120, v121
	v_cvt_pk_bf16_f32 v127, v122, v123
	global_store_dwordx4 v[218:219], v[124:127], off
	v_and_b32_e32 v241, 0xffff0000, v124
	v_lshlrev_b32_e32 v242, 16, v124
	v_mul_f32_e32 v241, v241, v241
	v_fmac_f32_e32 v241, v242, v242
	v_mov_b32_e32 v240, v241
	v_and_b32_e32 v241, 0xffff0000, v125
	v_lshlrev_b32_e32 v242, 16, v125
	v_mul_f32_e32 v241, v241, v241
	v_fmac_f32_e32 v241, v242, v242
	v_add_f32_e32 v240, v240, v241
	v_and_b32_e32 v241, 0xffff0000, v126
	v_lshlrev_b32_e32 v242, 16, v126
	v_mul_f32_e32 v241, v241, v241
	v_fmac_f32_e32 v241, v242, v242
	v_add_f32_e32 v240, v240, v241
	v_and_b32_e32 v241, 0xffff0000, v127
	v_lshlrev_b32_e32 v242, 16, v127
	v_mul_f32_e32 v241, v241, v241
	v_fmac_f32_e32 v241, v242, v242
	v_add_f32_e32 v240, v240, v241
	v_lshlrev_b32_e32 v241, 16, v132
	v_and_b32_e32 v242, 0xffff0000, v132
	v_add_f32_e32 v116, v116, v241
	v_add_f32_e32 v117, v117, v242
	v_lshlrev_b32_e32 v241, 16, v133
	v_and_b32_e32 v242, 0xffff0000, v133
	v_add_f32_e32 v118, v118, v241
	v_add_f32_e32 v119, v119, v242
	v_lshlrev_b32_e32 v241, 16, v134
	v_and_b32_e32 v242, 0xffff0000, v134
	v_add_f32_e32 v112, v112, v241
	v_add_f32_e32 v113, v113, v242
	v_lshlrev_b32_e32 v241, 16, v135
	v_and_b32_e32 v242, 0xffff0000, v135
	v_add_f32_e32 v114, v114, v241
	v_add_f32_e32 v115, v115, v242
	v_cvt_pk_bf16_f32 v116, v116, v117
	v_cvt_pk_bf16_f32 v117, v118, v119
	v_cvt_pk_bf16_f32 v118, v112, v113
	v_cvt_pk_bf16_f32 v119, v114, v115
	global_store_dwordx4 v[218:219], v[116:119], off offset:256
	v_and_b32_e32 v241, 0xffff0000, v116
	v_lshlrev_b32_e32 v242, 16, v116
	v_mul_f32_e32 v241, v241, v241
	v_fmac_f32_e32 v241, v242, v242
	v_add_f32_e32 v240, v240, v241
	v_and_b32_e32 v241, 0xffff0000, v117
	v_lshlrev_b32_e32 v242, 16, v117
	v_mul_f32_e32 v241, v241, v241
	v_fmac_f32_e32 v241, v242, v242
	v_add_f32_e32 v240, v240, v241
	v_and_b32_e32 v241, 0xffff0000, v118
	v_lshlrev_b32_e32 v242, 16, v118
	v_mul_f32_e32 v241, v241, v241
	v_fmac_f32_e32 v241, v242, v242
	v_add_f32_e32 v240, v240, v241
	v_and_b32_e32 v241, 0xffff0000, v119
	v_lshlrev_b32_e32 v242, 16, v119
	v_mul_f32_e32 v241, v241, v241
	v_fmac_f32_e32 v241, v242, v242
	v_add_f32_e32 v240, v240, v241
	v_lshl_add_u64 v[218:219], v[218:219], 0, s[98:99]
	ds_bpermute_b32 v244, v226, v240
	s_waitcnt lgkmcnt(0)
	v_add_f32_e32 v244, v240, v244
	ds_bpermute_b32 v245, v227, v244
	s_waitcnt lgkmcnt(0)
; #define ER_LOAD(q) do { _Pragma("unroll") for (int bj = 0; bj < 2; ++bj) t[(q) & 3][bj] = *(const u32x4*)(base + ER_OFF(q, bj)); } while (0)
; #define ER_ADD(q) do { _Pragma("unroll") for (int bj = 0; bj < 2; ++bj) { f32x4& a0 = acc[(q) >> 2][bj][(q) & 3][0]; f32x4& a1 = acc[(q) >> 2][bj][(q) & 3][1]; const u32x4 p = t[(q) & 3][bj]; \
;             a0[0] += bf_lo(p.x); a0[1] += bf_hi(p.x); a0[2] += bf_lo(p.y); a0[3] += bf_hi(p.y); a1[0] += bf_lo(p.z); a1[1] += bf_hi(p.z); a1[2] += bf_lo(p.w); a1[3] += bf_hi(p.w); } } while (0)
;     __device__ __forceinline__ void operator()(f32x4 (&acc)[2][2][4][2], const Unit& u, int wr, int wc, int fr, int fq) const {
;         const int row0 = u.pm * BM + wr * 64 + fr, col0 = u.pn * BM + wc * 32 + 8 * fq; const unsigned off0 = (unsigned)row0 * 1024u + (unsigned)col0;
;         u32x4 t[4][2];
;     ...
; #pragma unroll
;         for (int q = 0; q < 4; ++q) ER_LOAD(q);
; #pragma unroll
;         for (int q = 0; q < 4; ++q) ER_ADD(q);
; #pragma unroll
;         for (int q = 4; q < 8; ++q) ER_LOAD(q);
; #pragma unroll
;         for (int q = 0; q < 4; ++q) ER_STORE(q);
; #pragma unroll
;         for (int q = 4; q < 8; ++q) { ER_ADD(q); ER_STORE(q); }
	v_add_f32_e32 v244, v244, v245
	v_mul_f32_e32 v244, 0x49800000, v244
	v_trunc_f32_e32 v244, v244
	v_mul_f32_e32 v245, 0x2f800000, v244
	v_floor_f32_e32 v245, v245
	v_fmac_f32_e32 v244, 0xcf800000, v245
	v_cvt_u32_f32_e32 v245, v245
	v_cvt_u32_f32_e32 v244, v244
	s_and_saveexec_b64 s[10:11], vcc
	global_atomic_add_x2 v[220:221], v[244:245], off
	s_or_b64 exec, exec, s[10:11]
	s_waitcnt vmcnt(15)
	v_lshlrev_b32_e32 v241, 16, v136
	v_and_b32_e32 v242, 0xffff0000, v136
	v_add_f32_e32 v108, v108, v241
	v_add_f32_e32 v109, v109, v242
	v_lshlrev_b32_e32 v241, 16, v137
	v_and_b32_e32 v242, 0xffff0000, v137
	v_add_f32_e32 v110, v110, v241
	v_add_f32_e32 v111, v111, v242
	v_lshlrev_b32_e32 v241, 16, v138
	v_and_b32_e32 v242, 0xffff0000, v138
	v_add_f32_e32 v104, v104, v241
	v_add_f32_e32 v105, v105, v242
	v_lshlrev_b32_e32 v241, 16, v139
	v_and_b32_e32 v242, 0xffff0000, v139
	v_add_f32_e32 v106, v106, v241
	v_add_f32_e32 v107, v107, v242
	v_cvt_pk_bf16_f32 v108, v108, v109
	v_cvt_pk_bf16_f32 v109, v110, v111
	v_cvt_pk_bf16_f32 v110, v104, v105
	v_cvt_pk_bf16_f32 v111, v106, v107
	global_store_dwordx4 v[218:219], v[108:111], off
	v_and_b32_e32 v241, 0xffff0000, v108
	v_lshlrev_b32_e32 v242, 16, v108
	v_mul_f32_e32 v241, v241, v241
	v_fmac_f32_e32 v241, v242, v242
	v_mov_b32_e32 v240, v241
	v_and_b32_e32 v241, 0xffff0000, v109
	v_lshlrev_b32_e32 v242, 16, v109
	v_mul_f32_e32 v241, v241, v241
	v_fmac_f32_e32 v241, v242, v242
	v_add_f32_e32 v240, v240, v241
	v_and_b32_e32 v241, 0xffff0000, v110
	v_lshlrev_b32_e32 v242, 16, v110
	v_mul_f32_e32 v241, v241, v241
	v_fmac_f32_e32 v241, v242, v242
	v_add_f32_e32 v240, v240, v241
	v_and_b32_e32 v241, 0xffff0000, v111
	v_lshlrev_b32_e32 v242, 16, v111
	v_mul_f32_e32 v241, v241, v241
	v_fmac_f32_e32 v241, v242, v242
	v_add_f32_e32 v240, v240, v241
	v_lshlrev_b32_e32 v241, 16, v140
	v_and_b32_e32 v242, 0xffff0000, v140
	v_add_f32_e32 v100, v100, v241
	v_add_f32_e32 v101, v101, v242
	v_lshlrev_b32_e32 v241, 16, v141
	v_and_b32_e32 v242, 0xffff0000, v141
	v_add_f32_e32 v102, v102, v241
	v_add_f32_e32 v103, v103, v242
	v_lshlrev_b32_e32 v241, 16, v142
	v_and_b32_e32 v242, 0xffff0000, v142
	v_add_f32_e32 v96, v96, v241
	v_add_f32_e32 v97, v97, v242
	v_lshlrev_b32_e32 v241, 16, v143
	v_and_b32_e32 v242, 0xffff0000, v143
	v_add_f32_e32 v98, v98, v241
	v_add_f32_e32 v99, v99, v242
	v_cvt_pk_bf16_f32 v100, v100, v101
	v_cvt_pk_bf16_f32 v101, v102, v103
	v_cvt_pk_bf16_f32 v102, v96, v97
	v_cvt_pk_bf16_f32 v103, v98, v99
	global_store_dwordx4 v[218:219], v[100:103], off offset:256
	v_and_b32_e32 v241, 0xffff0000, v100
	v_lshlrev_b32_e32 v242, 16, v100
	v_mul_f32_e32 v241, v241, v241
	v_fmac_f32_e32 v241, v242, v242
	v_add_f32_e32 v240, v240, v241
	v_and_b32_e32 v241, 0xffff0000, v101
	v_lshlrev_b32_e32 v242, 16, v101
	v_mul_f32_e32 v241, v241, v241
	v_fmac_f32_e32 v241, v242, v242
	v_add_f32_e32 v240, v240, v241
	v_and_b32_e32 v241, 0xffff0000, v102
	v_lshlrev_b32_e32 v242, 16, v102
	v_mul_f32_e32 v241, v241, v241
	v_fmac_f32_e32 v241, v242, v242
	v_add_f32_e32 v240, v240, v241
	v_and_b32_e32 v241, 0xffff0000, v103
	v_lshlrev_b32_e32 v242, 16, v103
	v_mul_f32_e32 v241, v241, v241
	v_fmac_f32_e32 v241, v242, v242
	v_add_f32_e32 v240, v240, v241
	v_lshl_add_u64 v[218:219], v[218:219], 0, s[98:99]
	ds_bpermute_b32 v244, v226, v240
	s_waitcnt lgkmcnt(0)
	v_add_f32_e32 v244, v240, v244
	ds_bpermute_b32 v245, v227, v244
	s_waitcnt lgkmcnt(0)
	v_add_f32_e32 v244, v244, v245
	v_mul_f32_e32 v244, 0x49800000, v244
	v_trunc_f32_e32 v244, v244
	v_mul_f32_e32 v245, 0x2f800000, v244
	v_floor_f32_e32 v245, v245
	v_fmac_f32_e32 v244, 0xcf800000, v245
	v_cvt_u32_f32_e32 v245, v245
	v_cvt_u32_f32_e32 v244, v244
	s_and_saveexec_b64 s[10:11], vcc
	global_atomic_add_x2 v[220:221], v[244:245], off offset:128
	s_or_b64 exec, exec, s[10:11]
	s_waitcnt vmcnt(16)
	v_lshlrev_b32_e32 v241, 16, v144
	v_and_b32_e32 v242, 0xffff0000, v144
	v_add_f32_e32 v92, v92, v241
	v_add_f32_e32 v93, v93, v242
	v_lshlrev_b32_e32 v241, 16, v145
	v_and_b32_e32 v242, 0xffff0000, v145
	v_add_f32_e32 v94, v94, v241
	v_add_f32_e32 v95, v95, v242
	v_lshlrev_b32_e32 v241, 16, v146
	v_and_b32_e32 v242, 0xffff0000, v146
	v_add_f32_e32 v88, v88, v241
	v_add_f32_e32 v89, v89, v242
	v_lshlrev_b32_e32 v241, 16, v147
	v_and_b32_e32 v242, 0xffff0000, v147
	v_add_f32_e32 v90, v90, v241
	v_add_f32_e32 v91, v91, v242
	v_cvt_pk_bf16_f32 v92, v92, v93
	v_cvt_pk_bf16_f32 v93, v94, v95
	v_cvt_pk_bf16_f32 v94, v88, v89
	v_cvt_pk_bf16_f32 v95, v90, v91
	global_store_dwordx4 v[218:219], v[92:95], off
	v_and_b32_e32 v241, 0xffff0000, v92
	v_lshlrev_b32_e32 v242, 16, v92
	v_mul_f32_e32 v241, v241, v241
	v_fmac_f32_e32 v241, v242, v242
	v_mov_b32_e32 v240, v241
	v_and_b32_e32 v241, 0xffff0000, v93
	v_lshlrev_b32_e32 v242, 16, v93
	v_mul_f32_e32 v241, v241, v241
	v_fmac_f32_e32 v241, v242, v242
	v_add_f32_e32 v240, v240, v241
	v_and_b32_e32 v241, 0xffff0000, v94
	v_lshlrev_b32_e32 v242, 16, v94
	v_mul_f32_e32 v241, v241, v241
	v_fmac_f32_e32 v241, v242, v242
	v_add_f32_e32 v240, v240, v241
	v_and_b32_e32 v241, 0xffff0000, v95
	v_lshlrev_b32_e32 v242, 16, v95
	v_mul_f32_e32 v241, v241, v241
	v_fmac_f32_e32 v241, v242, v242
	v_add_f32_e32 v240, v240, v241
	v_lshlrev_b32_e32 v241, 16, v148
	v_and_b32_e32 v242, 0xffff0000, v148
	v_add_f32_e32 v84, v84, v241
	v_add_f32_e32 v85, v85, v242
	v_lshlrev_b32_e32 v241, 16, v149
	v_and_b32_e32 v242, 0xffff0000, v149
	v_add_f32_e32 v86, v86, v241
	v_add_f32_e32 v87, v87, v242
	v_lshlrev_b32_e32 v241, 16, v150
	v_and_b32_e32 v242, 0xffff0000, v150
	v_add_f32_e32 v80, v80, v241
	v_add_f32_e32 v81, v81, v242
	v_lshlrev_b32_e32 v241, 16, v151
	v_and_b32_e32 v242, 0xffff0000, v151
	v_add_f32_e32 v82, v82, v241
	v_add_f32_e32 v83, v83, v242
	v_cvt_pk_bf16_f32 v84, v84, v85
	v_cvt_pk_bf16_f32 v85, v86, v87
	v_cvt_pk_bf16_f32 v86, v80, v81
	v_cvt_pk_bf16_f32 v87, v82, v83
	global_store_dwordx4 v[218:219], v[84:87], off offset:256
	v_and_b32_e32 v241, 0xffff0000, v84
	v_lshlrev_b32_e32 v242, 16, v84
	v_mul_f32_e32 v241, v241, v241
	v_fmac_f32_e32 v241, v242, v242
	v_add_f32_e32 v240, v240, v241
	v_and_b32_e32 v241, 0xffff0000, v85
	v_lshlrev_b32_e32 v242, 16, v85
	v_mul_f32_e32 v241, v241, v241
	v_fmac_f32_e32 v241, v242, v242
	v_add_f32_e32 v240, v240, v241
	v_and_b32_e32 v241, 0xffff0000, v86
	v_lshlrev_b32_e32 v242, 16, v86
	v_mul_f32_e32 v241, v241, v241
	v_fmac_f32_e32 v241, v242, v242
	v_add_f32_e32 v240, v240, v241
	v_and_b32_e32 v241, 0xffff0000, v87
	v_lshlrev_b32_e32 v242, 16, v87
	v_mul_f32_e32 v241, v241, v241
	v_fmac_f32_e32 v241, v242, v242
	v_add_f32_e32 v240, v240, v241
	v_lshl_add_u64 v[218:219], v[218:219], 0, s[98:99]
	ds_bpermute_b32 v244, v226, v240
	s_waitcnt lgkmcnt(0)
; #define ER_LOAD(q) do { _Pragma("unroll") for (int bj = 0; bj < 2; ++bj) t[(q) & 3][bj] = *(const u32x4*)(base + ER_OFF(q, bj)); } while (0)
; #define ER_ADD(q) do { _Pragma("unroll") for (int bj = 0; bj < 2; ++bj) { f32x4& a0 = acc[(q) >> 2][bj][(q) & 3][0]; f32x4& a1 = acc[(q) >> 2][bj][(q) & 3][1]; const u32x4 p = t[(q) & 3][bj]; \
;             a0[0] += bf_lo(p.x); a0[1] += bf_hi(p.x); a0[2] += bf_lo(p.y); a0[3] += bf_hi(p.y); a1[0] += bf_lo(p.z); a1[1] += bf_hi(p.z); a1[2] += bf_lo(p.w); a1[3] += bf_hi(p.w); } } while (0)
;     __device__ __forceinline__ void operator()(f32x4 (&acc)[2][2][4][2], const Unit& u, int wr, int wc, int fr, int fq) const {
;         const int row0 = u.pm * BM + wr * 64 + fr, col0 = u.pn * BM + wc * 32 + 8 * fq; const unsigned off0 = (unsigned)row0 * 1024u + (unsigned)col0;
;         u32x4 t[4][2];
;     ...
; #pragma unroll
;         for (int q = 0; q < 4; ++q) ER_LOAD(q);
; #pragma unroll
;         for (int q = 0; q < 4; ++q) ER_ADD(q);
; #pragma unroll
;         for (int q = 4; q < 8; ++q) ER_LOAD(q);
; #pragma unroll
;         for (int q = 0; q < 4; ++q) ER_STORE(q);
; #pragma unroll
;         for (int q = 4; q < 8; ++q) { ER_ADD(q); ER_STORE(q); }
	v_add_f32_e32 v244, v240, v244
	ds_bpermute_b32 v245, v227, v244
	s_waitcnt lgkmcnt(0)
	v_add_f32_e32 v244, v244, v245
	v_mul_f32_e32 v244, 0x49800000, v244
	v_trunc_f32_e32 v244, v244
	v_mul_f32_e32 v245, 0x2f800000, v244
	v_floor_f32_e32 v245, v245
	v_fmac_f32_e32 v244, 0xcf800000, v245
	v_cvt_u32_f32_e32 v245, v245
	v_cvt_u32_f32_e32 v244, v244
	s_and_saveexec_b64 s[10:11], vcc
	global_atomic_add_x2 v[220:221], v[244:245], off offset:256
	s_or_b64 exec, exec, s[10:11]
	s_waitcnt vmcnt(17)
	v_lshlrev_b32_e32 v241, 16, v152
	v_and_b32_e32 v242, 0xffff0000, v152
	v_add_f32_e32 v76, v76, v241
	v_add_f32_e32 v77, v77, v242
	v_lshlrev_b32_e32 v241, 16, v153
	v_and_b32_e32 v242, 0xffff0000, v153
	v_add_f32_e32 v78, v78, v241
	v_add_f32_e32 v79, v79, v242
	v_lshlrev_b32_e32 v241, 16, v154
	v_and_b32_e32 v242, 0xffff0000, v154
	v_add_f32_e32 v72, v72, v241
	v_add_f32_e32 v73, v73, v242
	v_lshlrev_b32_e32 v241, 16, v155
	v_and_b32_e32 v242, 0xffff0000, v155
	v_add_f32_e32 v74, v74, v241
	v_add_f32_e32 v75, v75, v242
	v_cvt_pk_bf16_f32 v76, v76, v77
	v_cvt_pk_bf16_f32 v77, v78, v79
	v_cvt_pk_bf16_f32 v78, v72, v73
	v_cvt_pk_bf16_f32 v79, v74, v75
	global_store_dwordx4 v[218:219], v[76:79], off
	v_and_b32_e32 v241, 0xffff0000, v76
	v_lshlrev_b32_e32 v242, 16, v76
	v_mul_f32_e32 v241, v241, v241
	v_fmac_f32_e32 v241, v242, v242
	v_mov_b32_e32 v240, v241
	v_and_b32_e32 v241, 0xffff0000, v77
	v_lshlrev_b32_e32 v242, 16, v77
	v_mul_f32_e32 v241, v241, v241
	v_fmac_f32_e32 v241, v242, v242
	v_add_f32_e32 v240, v240, v241
	v_and_b32_e32 v241, 0xffff0000, v78
	v_lshlrev_b32_e32 v242, 16, v78
	v_mul_f32_e32 v241, v241, v241
	v_fmac_f32_e32 v241, v242, v242
	v_add_f32_e32 v240, v240, v241
	v_and_b32_e32 v241, 0xffff0000, v79
	v_lshlrev_b32_e32 v242, 16, v79
	v_mul_f32_e32 v241, v241, v241
	v_fmac_f32_e32 v241, v242, v242
	v_add_f32_e32 v240, v240, v241
	v_lshlrev_b32_e32 v241, 16, v156
	v_and_b32_e32 v242, 0xffff0000, v156
	v_add_f32_e32 v68, v68, v241
	v_add_f32_e32 v69, v69, v242
	v_lshlrev_b32_e32 v241, 16, v157
	v_and_b32_e32 v242, 0xffff0000, v157
	v_add_f32_e32 v70, v70, v241
	v_add_f32_e32 v71, v71, v242
	v_lshlrev_b32_e32 v241, 16, v158
	v_and_b32_e32 v242, 0xffff0000, v158
	v_add_f32_e32 v64, v64, v241
	v_add_f32_e32 v65, v65, v242
	v_lshlrev_b32_e32 v241, 16, v159
	v_and_b32_e32 v242, 0xffff0000, v159
	v_add_f32_e32 v66, v66, v241
	v_add_f32_e32 v67, v67, v242
	v_cvt_pk_bf16_f32 v68, v68, v69
	v_cvt_pk_bf16_f32 v69, v70, v71
	v_cvt_pk_bf16_f32 v70, v64, v65
	v_cvt_pk_bf16_f32 v71, v66, v67
	global_store_dwordx4 v[218:219], v[68:71], off offset:256
	v_and_b32_e32 v241, 0xffff0000, v68
	v_lshlrev_b32_e32 v242, 16, v68
	v_mul_f32_e32 v241, v241, v241
	v_fmac_f32_e32 v241, v242, v242
	v_add_f32_e32 v240, v240, v241
	v_and_b32_e32 v241, 0xffff0000, v69
	v_lshlrev_b32_e32 v242, 16, v69
	v_mul_f32_e32 v241, v241, v241
	v_fmac_f32_e32 v241, v242, v242
	v_add_f32_e32 v240, v240, v241
	v_and_b32_e32 v241, 0xffff0000, v70
	v_lshlrev_b32_e32 v242, 16, v70
	v_mul_f32_e32 v241, v241, v241
	v_fmac_f32_e32 v241, v242, v242
	v_add_f32_e32 v240, v240, v241
	v_and_b32_e32 v241, 0xffff0000, v71
	v_lshlrev_b32_e32 v242, 16, v71
	v_mul_f32_e32 v241, v241, v241
	v_fmac_f32_e32 v241, v242, v242
	v_add_f32_e32 v240, v240, v241
	v_lshl_add_u64 v[218:219], v[218:219], 0, s[98:99]
	v_lshl_add_u64 v[218:219], v[218:219], 0, s[98:99]
	v_lshl_add_u64 v[218:219], v[218:219], 0, s[98:99]
	v_lshl_add_u64 v[218:219], v[218:219], 0, s[98:99]
	v_lshl_add_u64 v[218:219], v[218:219], 0, s[98:99]
	ds_bpermute_b32 v244, v226, v240
	s_waitcnt lgkmcnt(0)
	v_add_f32_e32 v244, v240, v244
	ds_bpermute_b32 v245, v227, v244
	s_waitcnt lgkmcnt(0)
	v_add_f32_e32 v244, v244, v245
	v_mul_f32_e32 v244, 0x49800000, v244
	v_trunc_f32_e32 v244, v244
	v_mul_f32_e32 v245, 0x2f800000, v244
	v_floor_f32_e32 v245, v245
	v_fmac_f32_e32 v244, 0xcf800000, v245
	v_cvt_u32_f32_e32 v245, v245
	v_cvt_u32_f32_e32 v244, v244
	s_and_saveexec_b64 s[10:11], vcc
	global_atomic_add_x2 v[220:221], v[244:245], off offset:384
	s_or_b64 exec, exec, s[10:11]
	s_waitcnt vmcnt(18)
	v_lshlrev_b32_e32 v241, 16, v160
	v_and_b32_e32 v242, 0xffff0000, v160
	v_add_f32_e32 v60, v60, v241
	v_add_f32_e32 v61, v61, v242
	v_lshlrev_b32_e32 v241, 16, v161
	v_and_b32_e32 v242, 0xffff0000, v161
	v_add_f32_e32 v62, v62, v241
	v_add_f32_e32 v63, v63, v242
	v_lshlrev_b32_e32 v241, 16, v162
	v_and_b32_e32 v242, 0xffff0000, v162
	v_add_f32_e32 v56, v56, v241
	v_add_f32_e32 v57, v57, v242
	v_lshlrev_b32_e32 v241, 16, v163
	v_and_b32_e32 v242, 0xffff0000, v163
	v_add_f32_e32 v58, v58, v241
	v_add_f32_e32 v59, v59, v242
	v_cvt_pk_bf16_f32 v60, v60, v61
	v_cvt_pk_bf16_f32 v61, v62, v63
	v_cvt_pk_bf16_f32 v62, v56, v57
	v_cvt_pk_bf16_f32 v63, v58, v59
	global_store_dwordx4 v[218:219], v[60:63], off
	v_and_b32_e32 v241, 0xffff0000, v60
	v_lshlrev_b32_e32 v242, 16, v60
	v_mul_f32_e32 v241, v241, v241
	v_fmac_f32_e32 v241, v242, v242
	v_mov_b32_e32 v240, v241
	v_and_b32_e32 v241, 0xffff0000, v61
	v_lshlrev_b32_e32 v242, 16, v61
	v_mul_f32_e32 v241, v241, v241
	v_fmac_f32_e32 v241, v242, v242
	v_add_f32_e32 v240, v240, v241
	v_and_b32_e32 v241, 0xffff0000, v62
	v_lshlrev_b32_e32 v242, 16, v62
	v_mul_f32_e32 v241, v241, v241
	v_fmac_f32_e32 v241, v242, v242
	v_add_f32_e32 v240, v240, v241
	v_and_b32_e32 v241, 0xffff0000, v63
	v_lshlrev_b32_e32 v242, 16, v63
	v_mul_f32_e32 v241, v241, v241
	v_fmac_f32_e32 v241, v242, v242
	v_add_f32_e32 v240, v240, v241
	v_lshlrev_b32_e32 v241, 16, v164
	v_and_b32_e32 v242, 0xffff0000, v164
	v_add_f32_e32 v52, v52, v241
	v_add_f32_e32 v53, v53, v242
	v_lshlrev_b32_e32 v241, 16, v165
	v_and_b32_e32 v242, 0xffff0000, v165
	v_add_f32_e32 v54, v54, v241
	v_add_f32_e32 v55, v55, v242
	v_lshlrev_b32_e32 v241, 16, v166
	v_and_b32_e32 v242, 0xffff0000, v166
	v_add_f32_e32 v48, v48, v241
	v_add_f32_e32 v49, v49, v242
	v_lshlrev_b32_e32 v241, 16, v167
	v_and_b32_e32 v242, 0xffff0000, v167
	v_add_f32_e32 v50, v50, v241
	v_add_f32_e32 v51, v51, v242
	v_cvt_pk_bf16_f32 v52, v52, v53
	v_cvt_pk_bf16_f32 v53, v54, v55
	v_cvt_pk_bf16_f32 v54, v48, v49
	v_cvt_pk_bf16_f32 v55, v50, v51
	global_store_dwordx4 v[218:219], v[52:55], off offset:256
	v_and_b32_e32 v241, 0xffff0000, v52
	v_lshlrev_b32_e32 v242, 16, v52
	v_mul_f32_e32 v241, v241, v241
	v_fmac_f32_e32 v241, v242, v242
	v_add_f32_e32 v240, v240, v241
	v_and_b32_e32 v241, 0xffff0000, v53
	v_lshlrev_b32_e32 v242, 16, v53
	v_mul_f32_e32 v241, v241, v241
	v_fmac_f32_e32 v241, v242, v242
	v_add_f32_e32 v240, v240, v241
	v_and_b32_e32 v241, 0xffff0000, v54
	v_lshlrev_b32_e32 v242, 16, v54
	v_mul_f32_e32 v241, v241, v241
	v_fmac_f32_e32 v241, v242, v242
	v_add_f32_e32 v240, v240, v241
	v_and_b32_e32 v241, 0xffff0000, v55
	v_lshlrev_b32_e32 v242, 16, v55
	v_mul_f32_e32 v241, v241, v241
	v_fmac_f32_e32 v241, v242, v242
	v_add_f32_e32 v240, v240, v241
	v_lshl_add_u64 v[218:219], v[218:219], 0, s[98:99]
	ds_bpermute_b32 v244, v226, v240
	s_waitcnt lgkmcnt(0)
; #define ER_LOAD(q) do { _Pragma("unroll") for (int bj = 0; bj < 2; ++bj) t[(q) & 3][bj] = *(const u32x4*)(base + ER_OFF(q, bj)); } while (0)
; #define ER_ADD(q) do { _Pragma("unroll") for (int bj = 0; bj < 2; ++bj) { f32x4& a0 = acc[(q) >> 2][bj][(q) & 3][0]; f32x4& a1 = acc[(q) >> 2][bj][(q) & 3][1]; const u32x4 p = t[(q) & 3][bj]; \
;             a0[0] += bf_lo(p.x); a0[1] += bf_hi(p.x); a0[2] += bf_lo(p.y); a0[3] += bf_hi(p.y); a1[0] += bf_lo(p.z); a1[1] += bf_hi(p.z); a1[2] += bf_lo(p.w); a1[3] += bf_hi(p.w); } } while (0)
;     __device__ __forceinline__ void operator()(f32x4 (&acc)[2][2][4][2], const Unit& u, int wr, int wc, int fr, int fq) const {
;         const int row0 = u.pm * BM + wr * 64 + fr, col0 = u.pn * BM + wc * 32 + 8 * fq; const unsigned off0 = (unsigned)row0 * 1024u + (unsigned)col0;
;         u32x4 t[4][2];
;     ...
; #pragma unroll
;         for (int q = 0; q < 4; ++q) ER_LOAD(q);
; #pragma unroll
;         for (int q = 0; q < 4; ++q) ER_ADD(q);
; #pragma unroll
;         for (int q = 4; q < 8; ++q) ER_LOAD(q);
; #pragma unroll
;         for (int q = 0; q < 4; ++q) ER_STORE(q);
; #pragma unroll
;         for (int q = 4; q < 8; ++q) { ER_ADD(q); ER_STORE(q); }
	v_add_f32_e32 v244, v240, v244
	ds_bpermute_b32 v245, v227, v244
	s_waitcnt lgkmcnt(0)
	v_add_f32_e32 v244, v244, v245
	v_mul_f32_e32 v244, 0x49800000, v244
	v_trunc_f32_e32 v244, v244
	v_mul_f32_e32 v245, 0x2f800000, v244
	v_floor_f32_e32 v245, v245
	v_fmac_f32_e32 v244, 0xcf800000, v245
	v_cvt_u32_f32_e32 v245, v245
	v_cvt_u32_f32_e32 v244, v244
	s_and_saveexec_b64 s[10:11], vcc
	global_atomic_add_x2 v[220:221], v[244:245], off offset:1024
	s_or_b64 exec, exec, s[10:11]
	s_waitcnt vmcnt(19)
	v_lshlrev_b32_e32 v241, 16, v192
	v_and_b32_e32 v242, 0xffff0000, v192
	v_add_f32_e32 v44, v44, v241
	v_add_f32_e32 v45, v45, v242
	v_lshlrev_b32_e32 v241, 16, v193
	v_and_b32_e32 v242, 0xffff0000, v193
	v_add_f32_e32 v46, v46, v241
	v_add_f32_e32 v47, v47, v242
	v_lshlrev_b32_e32 v241, 16, v194
	v_and_b32_e32 v242, 0xffff0000, v194
	v_add_f32_e32 v40, v40, v241
	v_add_f32_e32 v41, v41, v242
	v_lshlrev_b32_e32 v241, 16, v195
	v_and_b32_e32 v242, 0xffff0000, v195
	v_add_f32_e32 v42, v42, v241
	v_add_f32_e32 v43, v43, v242
	v_cvt_pk_bf16_f32 v44, v44, v45
	v_cvt_pk_bf16_f32 v45, v46, v47
	v_cvt_pk_bf16_f32 v46, v40, v41
	v_cvt_pk_bf16_f32 v47, v42, v43
	global_store_dwordx4 v[218:219], v[44:47], off
	v_and_b32_e32 v241, 0xffff0000, v44
	v_lshlrev_b32_e32 v242, 16, v44
	v_mul_f32_e32 v241, v241, v241
	v_fmac_f32_e32 v241, v242, v242
	v_mov_b32_e32 v240, v241
	v_and_b32_e32 v241, 0xffff0000, v45
	v_lshlrev_b32_e32 v242, 16, v45
	v_mul_f32_e32 v241, v241, v241
	v_fmac_f32_e32 v241, v242, v242
	v_add_f32_e32 v240, v240, v241
	v_and_b32_e32 v241, 0xffff0000, v46
	v_lshlrev_b32_e32 v242, 16, v46
	v_mul_f32_e32 v241, v241, v241
	v_fmac_f32_e32 v241, v242, v242
	v_add_f32_e32 v240, v240, v241
	v_and_b32_e32 v241, 0xffff0000, v47
	v_lshlrev_b32_e32 v242, 16, v47
	v_mul_f32_e32 v241, v241, v241
	v_fmac_f32_e32 v241, v242, v242
	v_add_f32_e32 v240, v240, v241
	v_lshlrev_b32_e32 v241, 16, v196
	v_and_b32_e32 v242, 0xffff0000, v196
	v_add_f32_e32 v36, v36, v241
	v_add_f32_e32 v37, v37, v242
	v_lshlrev_b32_e32 v241, 16, v197
	v_and_b32_e32 v242, 0xffff0000, v197
	v_add_f32_e32 v38, v38, v241
	v_add_f32_e32 v39, v39, v242
	v_lshlrev_b32_e32 v241, 16, v198
	v_and_b32_e32 v242, 0xffff0000, v198
	v_add_f32_e32 v32, v32, v241
	v_add_f32_e32 v33, v33, v242
	v_lshlrev_b32_e32 v241, 16, v199
	v_and_b32_e32 v242, 0xffff0000, v199
	v_add_f32_e32 v34, v34, v241
	v_add_f32_e32 v35, v35, v242
	v_cvt_pk_bf16_f32 v36, v36, v37
	v_cvt_pk_bf16_f32 v37, v38, v39
	v_cvt_pk_bf16_f32 v38, v32, v33
	v_cvt_pk_bf16_f32 v39, v34, v35
	global_store_dwordx4 v[218:219], v[36:39], off offset:256
	v_and_b32_e32 v241, 0xffff0000, v36
	v_lshlrev_b32_e32 v242, 16, v36
	v_mul_f32_e32 v241, v241, v241
	v_fmac_f32_e32 v241, v242, v242
	v_add_f32_e32 v240, v240, v241
	v_and_b32_e32 v241, 0xffff0000, v37
	v_lshlrev_b32_e32 v242, 16, v37
	v_mul_f32_e32 v241, v241, v241
	v_fmac_f32_e32 v241, v242, v242
	v_add_f32_e32 v240, v240, v241
	v_and_b32_e32 v241, 0xffff0000, v38
	v_lshlrev_b32_e32 v242, 16, v38
	v_mul_f32_e32 v241, v241, v241
	v_fmac_f32_e32 v241, v242, v242
	v_add_f32_e32 v240, v240, v241
	v_and_b32_e32 v241, 0xffff0000, v39
	v_lshlrev_b32_e32 v242, 16, v39
	v_mul_f32_e32 v241, v241, v241
	v_fmac_f32_e32 v241, v242, v242
	v_add_f32_e32 v240, v240, v241
	v_lshl_add_u64 v[218:219], v[218:219], 0, s[98:99]
	ds_bpermute_b32 v244, v226, v240
	s_waitcnt lgkmcnt(0)
	v_add_f32_e32 v244, v240, v244
	ds_bpermute_b32 v245, v227, v244
	s_waitcnt lgkmcnt(0)
	v_add_f32_e32 v244, v244, v245
	v_mul_f32_e32 v244, 0x49800000, v244
	v_trunc_f32_e32 v244, v244
	v_mul_f32_e32 v245, 0x2f800000, v244
	v_floor_f32_e32 v245, v245
	v_fmac_f32_e32 v244, 0xcf800000, v245
	v_cvt_u32_f32_e32 v245, v245
	v_cvt_u32_f32_e32 v244, v244
	s_and_saveexec_b64 s[10:11], vcc
	global_atomic_add_x2 v[220:221], v[244:245], off offset:1152
	s_or_b64 exec, exec, s[10:11]
	s_waitcnt vmcnt(20)
; #define ER_LOAD(q) do { _Pragma("unroll") for (int bj = 0; bj < 2; ++bj) t[(q) & 3][bj] = *(const u32x4*)(base + ER_OFF(q, bj)); } while (0)
; #define ER_ADD(q) do { _Pragma("unroll") for (int bj = 0; bj < 2; ++bj) { f32x4& a0 = acc[(q) >> 2][bj][(q) & 3][0]; f32x4& a1 = acc[(q) >> 2][bj][(q) & 3][1]; const u32x4 p = t[(q) & 3][bj]; \
;             a0[0] += bf_lo(p.x); a0[1] += bf_hi(p.x); a0[2] += bf_lo(p.y); a0[3] += bf_hi(p.y); a1[0] += bf_lo(p.z); a1[1] += bf_hi(p.z); a1[2] += bf_lo(p.w); a1[3] += bf_hi(p.w); } } while (0)
;     __device__ __forceinline__ void operator()(f32x4 (&acc)[2][2][4][2], const Unit& u, int wr, int wc, int fr, int fq) const {
;         const int row0 = u.pm * BM + wr * 64 + fr, col0 = u.pn * BM + wc * 32 + 8 * fq; const unsigned off0 = (unsigned)row0 * 1024u + (unsigned)col0;
;         u32x4 t[4][2];
;     ...
; #pragma unroll
;         for (int q = 0; q < 4; ++q) ER_LOAD(q);
; #pragma unroll
;         for (int q = 0; q < 4; ++q) ER_ADD(q);
; #pragma unroll
;         for (int q = 4; q < 8; ++q) ER_LOAD(q);
; #pragma unroll
;         for (int q = 0; q < 4; ++q) ER_STORE(q);
; #pragma unroll
;         for (int q = 4; q < 8; ++q) { ER_ADD(q); ER_STORE(q); }
	v_lshlrev_b32_e32 v241, 16, v200
	v_and_b32_e32 v242, 0xffff0000, v200
	v_add_f32_e32 v28, v28, v241
	v_add_f32_e32 v29, v29, v242
	v_lshlrev_b32_e32 v241, 16, v201
	v_and_b32_e32 v242, 0xffff0000, v201
	v_add_f32_e32 v30, v30, v241
	v_add_f32_e32 v31, v31, v242
	v_lshlrev_b32_e32 v241, 16, v202
	v_and_b32_e32 v242, 0xffff0000, v202
	v_add_f32_e32 v24, v24, v241
	v_add_f32_e32 v25, v25, v242
	v_lshlrev_b32_e32 v241, 16, v203
	v_and_b32_e32 v242, 0xffff0000, v203
	v_add_f32_e32 v26, v26, v241
	v_add_f32_e32 v27, v27, v242
	v_cvt_pk_bf16_f32 v28, v28, v29
	v_cvt_pk_bf16_f32 v29, v30, v31
	v_cvt_pk_bf16_f32 v30, v24, v25
	v_cvt_pk_bf16_f32 v31, v26, v27
	global_store_dwordx4 v[218:219], v[28:31], off
	v_and_b32_e32 v241, 0xffff0000, v28
	v_lshlrev_b32_e32 v242, 16, v28
	v_mul_f32_e32 v241, v241, v241
	v_fmac_f32_e32 v241, v242, v242
	v_mov_b32_e32 v240, v241
	v_and_b32_e32 v241, 0xffff0000, v29
	v_lshlrev_b32_e32 v242, 16, v29
	v_mul_f32_e32 v241, v241, v241
	v_fmac_f32_e32 v241, v242, v242
	v_add_f32_e32 v240, v240, v241
	v_and_b32_e32 v241, 0xffff0000, v30
	v_lshlrev_b32_e32 v242, 16, v30
	v_mul_f32_e32 v241, v241, v241
	v_fmac_f32_e32 v241, v242, v242
	v_add_f32_e32 v240, v240, v241
	v_and_b32_e32 v241, 0xffff0000, v31
	v_lshlrev_b32_e32 v242, 16, v31
	v_mul_f32_e32 v241, v241, v241
	v_fmac_f32_e32 v241, v242, v242
	v_add_f32_e32 v240, v240, v241
	v_lshlrev_b32_e32 v241, 16, v204
	v_and_b32_e32 v242, 0xffff0000, v204
	v_add_f32_e32 v20, v20, v241
	v_add_f32_e32 v21, v21, v242
	v_lshlrev_b32_e32 v241, 16, v205
	v_and_b32_e32 v242, 0xffff0000, v205
	v_add_f32_e32 v22, v22, v241
	v_add_f32_e32 v23, v23, v242
	v_lshlrev_b32_e32 v241, 16, v206
	v_and_b32_e32 v242, 0xffff0000, v206
	v_add_f32_e32 v16, v16, v241
	v_add_f32_e32 v17, v17, v242
	v_lshlrev_b32_e32 v241, 16, v207
	v_and_b32_e32 v242, 0xffff0000, v207
	v_add_f32_e32 v18, v18, v241
	v_add_f32_e32 v19, v19, v242
	v_cvt_pk_bf16_f32 v20, v20, v21
	v_cvt_pk_bf16_f32 v21, v22, v23
	v_cvt_pk_bf16_f32 v22, v16, v17
	v_cvt_pk_bf16_f32 v23, v18, v19
	global_store_dwordx4 v[218:219], v[20:23], off offset:256
	v_and_b32_e32 v241, 0xffff0000, v20
	v_lshlrev_b32_e32 v242, 16, v20
	v_mul_f32_e32 v241, v241, v241
	v_fmac_f32_e32 v241, v242, v242
	v_add_f32_e32 v240, v240, v241
	v_and_b32_e32 v241, 0xffff0000, v21
	v_lshlrev_b32_e32 v242, 16, v21
	v_mul_f32_e32 v241, v241, v241
	v_fmac_f32_e32 v241, v242, v242
	v_add_f32_e32 v240, v240, v241
	v_and_b32_e32 v241, 0xffff0000, v22
	v_lshlrev_b32_e32 v242, 16, v22
	v_mul_f32_e32 v241, v241, v241
	v_fmac_f32_e32 v241, v242, v242
	v_add_f32_e32 v240, v240, v241
	v_and_b32_e32 v241, 0xffff0000, v23
	v_lshlrev_b32_e32 v242, 16, v23
	v_mul_f32_e32 v241, v241, v241
	v_fmac_f32_e32 v241, v242, v242
	v_add_f32_e32 v240, v240, v241
	v_lshl_add_u64 v[218:219], v[218:219], 0, s[98:99]
	ds_bpermute_b32 v244, v226, v240
	s_waitcnt lgkmcnt(0)
	v_add_f32_e32 v244, v240, v244
	ds_bpermute_b32 v245, v227, v244
	s_waitcnt lgkmcnt(0)
	v_add_f32_e32 v244, v244, v245
	v_mul_f32_e32 v244, 0x49800000, v244
	v_trunc_f32_e32 v244, v244
	v_mul_f32_e32 v245, 0x2f800000, v244
	v_floor_f32_e32 v245, v245
	v_fmac_f32_e32 v244, 0xcf800000, v245
	v_cvt_u32_f32_e32 v245, v245
	v_cvt_u32_f32_e32 v244, v244
	s_and_saveexec_b64 s[10:11], vcc
	global_atomic_add_x2 v[220:221], v[244:245], off offset:1280
	s_or_b64 exec, exec, s[10:11]
	s_waitcnt vmcnt(21)
	v_lshlrev_b32_e32 v241, 16, v208
	v_and_b32_e32 v242, 0xffff0000, v208
	v_add_f32_e32 v12, v12, v241
	v_add_f32_e32 v13, v13, v242
	v_lshlrev_b32_e32 v241, 16, v209
	v_and_b32_e32 v242, 0xffff0000, v209
	v_add_f32_e32 v14, v14, v241
	v_add_f32_e32 v15, v15, v242
	v_lshlrev_b32_e32 v241, 16, v210
	v_and_b32_e32 v242, 0xffff0000, v210
	v_add_f32_e32 v8, v8, v241
	v_add_f32_e32 v9, v9, v242
	v_lshlrev_b32_e32 v241, 16, v211
	v_and_b32_e32 v242, 0xffff0000, v211
	v_add_f32_e32 v10, v10, v241
	v_add_f32_e32 v11, v11, v242
	v_cvt_pk_bf16_f32 v12, v12, v13
	v_cvt_pk_bf16_f32 v13, v14, v15
	v_cvt_pk_bf16_f32 v14, v8, v9
	v_cvt_pk_bf16_f32 v15, v10, v11
	global_store_dwordx4 v[218:219], v[12:15], off
	v_and_b32_e32 v241, 0xffff0000, v12
	v_lshlrev_b32_e32 v242, 16, v12
	v_mul_f32_e32 v241, v241, v241
	v_fmac_f32_e32 v241, v242, v242
	v_mov_b32_e32 v240, v241
	v_and_b32_e32 v241, 0xffff0000, v13
	v_lshlrev_b32_e32 v242, 16, v13
	v_mul_f32_e32 v241, v241, v241
	v_fmac_f32_e32 v241, v242, v242
	v_add_f32_e32 v240, v240, v241
	v_and_b32_e32 v241, 0xffff0000, v14
	v_lshlrev_b32_e32 v242, 16, v14
	v_mul_f32_e32 v241, v241, v241
	v_fmac_f32_e32 v241, v242, v242
	v_add_f32_e32 v240, v240, v241
	v_and_b32_e32 v241, 0xffff0000, v15
	v_lshlrev_b32_e32 v242, 16, v15
	v_mul_f32_e32 v241, v241, v241
	v_fmac_f32_e32 v241, v242, v242
	v_add_f32_e32 v240, v240, v241
	v_lshlrev_b32_e32 v241, 16, v212
	v_and_b32_e32 v242, 0xffff0000, v212
	v_add_f32_e32 v4, v4, v241
	v_add_f32_e32 v5, v5, v242
	v_lshlrev_b32_e32 v241, 16, v213
	v_and_b32_e32 v242, 0xffff0000, v213
	v_add_f32_e32 v6, v6, v241
	v_add_f32_e32 v7, v7, v242
	v_lshlrev_b32_e32 v241, 16, v214
	v_and_b32_e32 v242, 0xffff0000, v214
	v_add_f32_e32 v0, v0, v241
	v_add_f32_e32 v1, v1, v242
	v_lshlrev_b32_e32 v241, 16, v215
	v_and_b32_e32 v242, 0xffff0000, v215
	v_add_f32_e32 v2, v2, v241
	v_add_f32_e32 v3, v3, v242
	v_cvt_pk_bf16_f32 v4, v4, v5
	v_cvt_pk_bf16_f32 v5, v6, v7
	v_cvt_pk_bf16_f32 v6, v0, v1
	v_cvt_pk_bf16_f32 v7, v2, v3
	global_store_dwordx4 v[218:219], v[4:7], off offset:256
	v_and_b32_e32 v241, 0xffff0000, v4
	v_lshlrev_b32_e32 v242, 16, v4
	v_mul_f32_e32 v241, v241, v241
	v_fmac_f32_e32 v241, v242, v242
	v_add_f32_e32 v240, v240, v241
	v_and_b32_e32 v241, 0xffff0000, v5
	v_lshlrev_b32_e32 v242, 16, v5
	v_mul_f32_e32 v241, v241, v241
	v_fmac_f32_e32 v241, v242, v242
	v_add_f32_e32 v240, v240, v241
	v_and_b32_e32 v241, 0xffff0000, v6
	v_lshlrev_b32_e32 v242, 16, v6
	v_mul_f32_e32 v241, v241, v241
	v_fmac_f32_e32 v241, v242, v242
	v_add_f32_e32 v240, v240, v241
	v_and_b32_e32 v241, 0xffff0000, v7
	v_lshlrev_b32_e32 v242, 16, v7
	v_mul_f32_e32 v241, v241, v241
	v_fmac_f32_e32 v241, v242, v242
	v_add_f32_e32 v240, v240, v241
	ds_bpermute_b32 v244, v226, v240
	s_waitcnt lgkmcnt(0)
	v_add_f32_e32 v244, v240, v244
	ds_bpermute_b32 v245, v227, v244
	s_waitcnt lgkmcnt(0)
	v_add_f32_e32 v244, v244, v245
	v_mul_f32_e32 v244, 0x49800000, v244
	v_trunc_f32_e32 v244, v244
	v_mul_f32_e32 v245, 0x2f800000, v244
	v_floor_f32_e32 v245, v245
	v_fmac_f32_e32 v244, 0xcf800000, v245
	v_cvt_u32_f32_e32 v245, v245
	v_cvt_u32_f32_e32 v244, v244
	s_and_saveexec_b64 s[10:11], vcc
	global_atomic_add_x2 v[220:221], v[244:245], off offset:1408
	s_or_b64 exec, exec, s[10:11]
	s_mov_b64 s[10:11], exec
	s_branch .LBB0_265
